# grid barriers: acquire L1 invalidate issued right after arrival (overlaps the wait) instead of after the generation word is observed
# speedup vs baseline: 1.0335x; 1.0123x over previous
.LBB0_53:
	s_or_b64 exec, exec, s[8:9]
	v_cvt_f32_u32_e32 v6, v4
	s_waitcnt vmcnt(0)
	v_readfirstlane_b32 s6, v5
	v_sub_u32_e32 v5, 0, v4
	v_rcp_iflag_f32_e32 v6, v6
	v_add_u32_e32 v7, s6, v3
	v_mul_f32_e32 v6, 0x4f7ffffe, v6
	v_cvt_u32_f32_e32 v6, v6
	v_mul_lo_u32 v3, v5, v6
	v_mul_hi_u32 v3, v6, v3
	v_add_u32_e32 v3, v6, v3
	v_mul_hi_u32 v3, v7, v3
	v_mul_lo_u32 v5, v3, v4
	v_sub_u32_e32 v5, v7, v5
	v_add_u32_e32 v6, 1, v3
	v_cmp_ge_u32_e32 vcc, v5, v4
	s_nop 1
	v_cndmask_b32_e32 v3, v3, v6, vcc
	v_sub_u32_e32 v6, v5, v4
	v_cndmask_b32_e32 v5, v5, v6, vcc
	v_add_u32_e32 v6, 1, v3
	v_cmp_ge_u32_e32 vcc, v5, v4
	v_add_u32_e32 v5, 1, v7
	s_nop 0
	v_cndmask_b32_e32 v3, v3, v6, vcc
	v_mul_lo_u32 v6, v4, v3
	v_add_u32_e32 v4, v6, v4
	v_cmp_ne_u32_e32 vcc, v5, v4
	s_and_saveexec_b64 s[6:7], vcc
	s_xor_b64 s[6:7], exec, s[6:7]
	s_cbranch_execz .LBB0_67
	s_movk_i32 s8, 0xd40
	buffer_inv sc1
	s_mov_b32 s9, 0
	s_lshl_b64 s[8:9], s[8:9], 2
	s_add_u32 s10, s4, s8
	s_addc_u32 s11, s5, s9
	s_waitcnt lgkmcnt(0)
	v_mov_b32_e32 v2, 0
	global_load_dword v4, v2, s[10:11] sc1
	s_waitcnt vmcnt(0)
	v_cmp_eq_u32_e32 vcc, v4, v3
	s_and_saveexec_b64 s[8:9], vcc
	s_cbranch_execz .LBB0_66
	s_mov_b32 s12, 1
	s_mov_b64 s[18:19], 0
	s_branch .LBB0_57

.LBB0_66:
	s_or_b64 exec, exec, s[8:9]
	s_waitcnt vmcnt(0)
	s_waitcnt vmcnt(0)
.LBB0_67:
	s_andn2_saveexec_b64 s[6:7], s[6:7]
	s_cbranch_execz .LBB0_87
	s_mov_b64 s[6:7], exec
	buffer_wbl2 sc1
	buffer_inv sc1
	s_waitcnt lgkmcnt(0)
	s_waitcnt vmcnt(0)
	v_mbcnt_lo_u32_b32 v3, s6, 0
	v_mbcnt_hi_u32_b32 v3, s7, v3
	v_cmp_eq_u32_e32 vcc, 0, v3
	s_and_saveexec_b64 s[8:9], vcc
	s_cbranch_execz .LBB0_70
	s_bcnt1_i32_b64 s6, s[6:7]
	v_mov_b32_e32 v4, 0x3000
	v_mov_b32_e32 v5, s6
	global_atomic_add v4, v4, v5, s[4:5] offset:1024 sc0

.LBB0_84:
	s_or_b64 exec, exec, s[6:7]
	s_mov_b64 s[6:7], exec
	v_mbcnt_lo_u32_b32 v2, s6, 0
	v_mbcnt_hi_u32_b32 v2, s7, v2
	s_mov_b32 s11, 0
	v_cmp_eq_u32_e32 vcc, 0, v2
	s_waitcnt vmcnt(0)
	s_and_saveexec_b64 s[8:9], vcc
	s_cbranch_execz .LBB0_86
	s_add_i32 s10, s3, 0x900
	s_lshl_b64 s[10:11], s[10:11], 2
	s_add_u32 s4, s4, s10
	s_addc_u32 s5, s5, s11
	s_bcnt1_i32_b64 s3, s[6:7]
	v_mov_b32_e32 v2, 0
	v_mov_b32_e32 v3, s3
	s_nop 0

.LBB0_230:
	s_or_b64 exec, exec, s[24:25]
	v_cvt_f32_u32_e32 v6, v4
	s_waitcnt vmcnt(0)
	v_readfirstlane_b32 s8, v5
	v_sub_u32_e32 v5, 0, v4
	v_rcp_iflag_f32_e32 v6, v6
	v_add_u32_e32 v7, s8, v3
	v_mul_f32_e32 v6, 0x4f7ffffe, v6
	v_cvt_u32_f32_e32 v6, v6
	v_mul_lo_u32 v3, v5, v6
	v_mul_hi_u32 v3, v6, v3
	v_add_u32_e32 v3, v6, v3
	v_mul_hi_u32 v3, v7, v3
	v_mul_lo_u32 v5, v3, v4
	v_sub_u32_e32 v5, v7, v5
	v_add_u32_e32 v6, 1, v3
	v_cmp_ge_u32_e32 vcc, v5, v4
	s_nop 1
	v_cndmask_b32_e32 v3, v3, v6, vcc
	v_sub_u32_e32 v6, v5, v4
	v_cndmask_b32_e32 v5, v5, v6, vcc
	v_add_u32_e32 v6, 1, v3
	v_cmp_ge_u32_e32 vcc, v5, v4
	v_add_u32_e32 v5, 1, v7
	s_nop 0
	v_cndmask_b32_e32 v3, v3, v6, vcc
	v_mul_lo_u32 v6, v4, v3
	v_add_u32_e32 v4, v6, v4
	v_cmp_ne_u32_e32 vcc, v5, v4
	s_and_saveexec_b64 s[8:9], vcc
	s_xor_b64 s[8:9], exec, s[8:9]
	s_cbranch_execz .LBB0_244
	s_movk_i32 s14, 0xd40
	buffer_inv sc1
	s_mov_b32 s15, 0
	s_lshl_b64 s[14:15], s[14:15], 2
	s_add_u32 s26, s6, s14
	s_addc_u32 s27, s7, s15
	s_waitcnt lgkmcnt(0)
	v_mov_b32_e32 v2, 0
	global_load_dword v4, v2, s[26:27] sc1
	s_waitcnt vmcnt(0)
	v_cmp_eq_u32_e32 vcc, v4, v3
	s_and_saveexec_b64 s[24:25], vcc
	s_cbranch_execz .LBB0_243
	s_mov_b32 s13, 1
	s_mov_b64 s[28:29], 0
	s_branch .LBB0_234

.LBB0_243:
	s_or_b64 exec, exec, s[24:25]
	s_waitcnt vmcnt(0)
	s_waitcnt vmcnt(0)
.LBB0_244:
	s_andn2_saveexec_b64 s[8:9], s[8:9]
	s_cbranch_execz .LBB0_264
	s_mov_b64 s[8:9], exec
	buffer_wbl2 sc1
	buffer_inv sc1
	s_waitcnt lgkmcnt(0)
	s_waitcnt vmcnt(0)
	v_mbcnt_lo_u32_b32 v3, s8, 0
	v_mbcnt_hi_u32_b32 v3, s9, v3
	v_cmp_eq_u32_e32 vcc, 0, v3
	s_and_saveexec_b64 s[24:25], vcc
	s_cbranch_execz .LBB0_247
	s_bcnt1_i32_b64 s8, s[8:9]
	v_mov_b32_e32 v4, 0x3000
	v_mov_b32_e32 v5, s8
	global_atomic_add v4, v4, v5, s[6:7] offset:1024 sc0

.LBB0_261:
	s_or_b64 exec, exec, s[8:9]
	s_mov_b64 s[8:9], exec
	v_mbcnt_lo_u32_b32 v2, s8, 0
	v_mbcnt_hi_u32_b32 v2, s9, v2
	s_mov_b32 s27, 0
	v_cmp_eq_u32_e32 vcc, 0, v2
	s_waitcnt vmcnt(0)
	s_and_saveexec_b64 s[24:25], vcc
	s_cbranch_execz .LBB0_263
	s_add_i32 s26, s12, 0x900
	s_lshl_b64 s[12:13], s[26:27], 2
	s_add_u32 s6, s6, s12
	s_addc_u32 s7, s7, s13
	s_bcnt1_i32_b64 s8, s[8:9]
	v_mov_b32_e32 v2, 0
	v_mov_b32_e32 v3, s8
	s_nop 0

.LBB0_348:
	s_or_b64 exec, exec, s[8:9]
	v_cvt_f32_u32_e32 v5, v3
	s_waitcnt vmcnt(0)
	v_readfirstlane_b32 s6, v4
	v_sub_u32_e32 v4, 0, v3
	v_rcp_iflag_f32_e32 v5, v5
	v_add_u32_e32 v6, s6, v2
	v_mul_f32_e32 v5, 0x4f7ffffe, v5
	v_cvt_u32_f32_e32 v5, v5
	v_mul_lo_u32 v2, v4, v5
	v_mul_hi_u32 v2, v5, v2
	v_add_u32_e32 v2, v5, v2
	v_mul_hi_u32 v2, v6, v2
	v_mul_lo_u32 v4, v2, v3
	v_sub_u32_e32 v4, v6, v4
	v_add_u32_e32 v5, 1, v2
	v_cmp_ge_u32_e32 vcc, v4, v3
	s_nop 1
	v_cndmask_b32_e32 v2, v2, v5, vcc
	v_sub_u32_e32 v5, v4, v3
	v_cndmask_b32_e32 v4, v4, v5, vcc
	v_add_u32_e32 v5, 1, v2
	v_cmp_ge_u32_e32 vcc, v4, v3
	v_add_u32_e32 v4, 1, v6
	s_nop 0
	v_cndmask_b32_e32 v2, v2, v5, vcc
	v_mul_lo_u32 v5, v3, v2
	v_add_u32_e32 v3, v5, v3
	v_cmp_ne_u32_e32 vcc, v4, v3
	s_and_saveexec_b64 s[6:7], vcc
	s_xor_b64 s[6:7], exec, s[6:7]
	s_cbranch_execz .LBB0_362
	s_movk_i32 s8, 0xd40
	buffer_inv sc1
	s_mov_b32 s9, 0
	s_lshl_b64 s[8:9], s[8:9], 2
	s_add_u32 s10, s4, s8
	s_addc_u32 s11, s5, s9
	s_waitcnt lgkmcnt(0)
	v_mov_b32_e32 v1, 0
	global_load_dword v3, v1, s[10:11] sc1
	s_waitcnt vmcnt(0)
	v_cmp_eq_u32_e32 vcc, v3, v2
	s_and_saveexec_b64 s[8:9], vcc
	s_cbranch_execz .LBB0_361
	s_mov_b32 s13, 1
	s_mov_b64 s[20:21], 0
	s_branch .LBB0_352

.LBB0_362:
	s_andn2_saveexec_b64 s[6:7], s[6:7]
	s_cbranch_execz .LBB0_382
	s_mov_b64 s[6:7], exec
	buffer_wbl2 sc1
	buffer_inv sc1
	s_waitcnt lgkmcnt(0)
	s_waitcnt vmcnt(0)
	v_mbcnt_lo_u32_b32 v2, s6, 0
	v_mbcnt_hi_u32_b32 v2, s7, v2
	v_cmp_eq_u32_e32 vcc, 0, v2
	s_and_saveexec_b64 s[8:9], vcc
	s_cbranch_execz .LBB0_365
	s_bcnt1_i32_b64 s6, s[6:7]
	v_mov_b32_e32 v3, 0x3000
	v_mov_b32_e32 v4, s6
	global_atomic_add v3, v3, v4, s[4:5] offset:1024 sc0

.LBB0_379:
	s_or_b64 exec, exec, s[6:7]
	s_mov_b64 s[6:7], exec
	v_mbcnt_lo_u32_b32 v1, s6, 0
	v_mbcnt_hi_u32_b32 v1, s7, v1
	s_mov_b32 s11, 0
	v_cmp_eq_u32_e32 vcc, 0, v1
	s_waitcnt vmcnt(0)
	s_and_saveexec_b64 s[8:9], vcc
	s_cbranch_execz .LBB0_381
	s_add_i32 s10, s12, 0x900
	s_lshl_b64 s[10:11], s[10:11], 2
	s_add_u32 s4, s4, s10
	s_addc_u32 s5, s5, s11
	s_bcnt1_i32_b64 s6, s[6:7]
	v_mov_b32_e32 v1, 0
	v_mov_b32_e32 v2, s6
	s_nop 0

.LBB0_483:
	s_or_b64 exec, exec, s[8:9]
	v_cvt_f32_u32_e32 v5, v3
	s_waitcnt vmcnt(0)
	v_readfirstlane_b32 s6, v4
	v_sub_u32_e32 v4, 0, v3
	v_rcp_iflag_f32_e32 v5, v5
	v_add_u32_e32 v6, s6, v2
	v_mul_f32_e32 v5, 0x4f7ffffe, v5
	v_cvt_u32_f32_e32 v5, v5
	v_mul_lo_u32 v2, v4, v5
	v_mul_hi_u32 v2, v5, v2
	v_add_u32_e32 v2, v5, v2
	v_mul_hi_u32 v2, v6, v2
	v_mul_lo_u32 v4, v2, v3
	v_sub_u32_e32 v4, v6, v4
	v_add_u32_e32 v5, 1, v2
	v_cmp_ge_u32_e32 vcc, v4, v3
	s_nop 1
	v_cndmask_b32_e32 v2, v2, v5, vcc
	v_sub_u32_e32 v5, v4, v3
	v_cndmask_b32_e32 v4, v4, v5, vcc
	v_add_u32_e32 v5, 1, v2
	v_cmp_ge_u32_e32 vcc, v4, v3
	v_add_u32_e32 v4, 1, v6
	s_nop 0
	v_cndmask_b32_e32 v2, v2, v5, vcc
	v_mul_lo_u32 v5, v3, v2
	v_add_u32_e32 v3, v5, v3
	v_cmp_ne_u32_e32 vcc, v4, v3
	s_and_saveexec_b64 s[6:7], vcc
	s_xor_b64 s[6:7], exec, s[6:7]
	s_cbranch_execz .LBB0_497
	s_movk_i32 s8, 0xd40
	buffer_inv sc1
	s_mov_b32 s9, 0
	s_lshl_b64 s[8:9], s[8:9], 2
	s_add_u32 s10, s4, s8
	s_addc_u32 s11, s5, s9
	s_waitcnt lgkmcnt(0)
	v_mov_b32_e32 v1, 0
	global_load_dword v3, v1, s[10:11] sc1
	s_waitcnt vmcnt(0)
	v_cmp_eq_u32_e32 vcc, v3, v2
	s_and_saveexec_b64 s[8:9], vcc
	s_cbranch_execz .LBB0_496
	s_mov_b32 s13, 1
	s_mov_b64 s[16:17], 0
	s_branch .LBB0_487

.LBB0_720:
	s_or_b64 exec, exec, s[36:37]
	v_cvt_f32_u32_e32 v10, v4
	s_waitcnt vmcnt(0)
	v_readfirstlane_b32 s8, v5
	v_sub_u32_e32 v5, 0, v4
	v_rcp_iflag_f32_e32 v10, v10
	v_add_u32_e32 v11, s8, v3
	v_mul_f32_e32 v10, 0x4f7ffffe, v10
	v_cvt_u32_f32_e32 v10, v10
	v_mul_lo_u32 v3, v5, v10
	v_mul_hi_u32 v3, v10, v3
	v_add_u32_e32 v3, v10, v3
	v_mul_hi_u32 v3, v11, v3
	v_mul_lo_u32 v5, v3, v4
	v_sub_u32_e32 v5, v11, v5
	v_add_u32_e32 v10, 1, v3
	v_cmp_ge_u32_e32 vcc, v5, v4
	s_nop 1
	v_cndmask_b32_e32 v3, v3, v10, vcc
	v_sub_u32_e32 v10, v5, v4
	v_cndmask_b32_e32 v5, v5, v10, vcc
	v_add_u32_e32 v10, 1, v3
	v_cmp_ge_u32_e32 vcc, v5, v4
	v_add_u32_e32 v5, 1, v11
	s_nop 0
	v_cndmask_b32_e32 v3, v3, v10, vcc
	v_mul_lo_u32 v10, v4, v3
	v_add_u32_e32 v4, v10, v4
	v_cmp_ne_u32_e32 vcc, v5, v4
	s_and_saveexec_b64 s[8:9], vcc
	s_xor_b64 s[8:9], exec, s[8:9]
	s_cbranch_execz .LBB0_734
	s_movk_i32 s26, 0xd40
	buffer_inv sc1
	s_lshl_b64 s[14:15], s[26:27], 2
	s_add_u32 s38, s6, s14
	s_addc_u32 s39, s7, s15
	s_waitcnt lgkmcnt(0)
	global_load_dword v1, v2, s[38:39] sc1
	s_waitcnt vmcnt(0)
	v_cmp_eq_u32_e32 vcc, v1, v3
	s_and_saveexec_b64 s[36:37], vcc
	s_cbranch_execz .LBB0_733
	s_mov_b32 s13, 1
	s_mov_b64 s[60:61], 0
	s_branch .LBB0_724

.LBB0_733:
	s_or_b64 exec, exec, s[36:37]
	s_waitcnt vmcnt(0)
	s_waitcnt vmcnt(0)
.LBB0_734:
	s_andn2_saveexec_b64 s[8:9], s[8:9]
	s_cbranch_execz .LBB0_754
	s_mov_b64 s[8:9], exec
	buffer_wbl2 sc1
	buffer_inv sc1
	s_waitcnt lgkmcnt(0)
	s_waitcnt vmcnt(0)
	v_mbcnt_lo_u32_b32 v3, s8, 0
	v_mbcnt_hi_u32_b32 v3, s9, v3
	v_cmp_eq_u32_e32 vcc, 0, v3
	s_and_saveexec_b64 s[36:37], vcc
	s_cbranch_execz .LBB0_737
	s_bcnt1_i32_b64 s8, s[8:9]
	v_mov_b32_e32 v4, s8
	global_atomic_add v4, v172, v4, s[6:7] offset:1024 sc0

.LBB0_751:
	s_or_b64 exec, exec, s[8:9]
	s_mov_b64 s[8:9], exec
	v_mbcnt_lo_u32_b32 v1, s8, 0
	v_mbcnt_hi_u32_b32 v1, s9, v1
	v_cmp_eq_u32_e32 vcc, 0, v1
	s_waitcnt vmcnt(0)
	s_and_saveexec_b64 s[36:37], vcc
	s_cbranch_execz .LBB0_753
	s_add_i32 s26, s12, 0x900
	s_lshl_b64 s[12:13], s[26:27], 2
	s_add_u32 s6, s6, s12
	s_addc_u32 s7, s7, s13
	s_bcnt1_i32_b64 s8, s[8:9]
	v_mov_b32_e32 v1, s8
	s_nop 0

.LBB0_775:
	s_or_b64 exec, exec, s[38:39]
	v_cvt_f32_u32_e32 v11, v5
	s_waitcnt vmcnt(0)
	v_readfirstlane_b32 s13, v10
	v_sub_u32_e32 v10, 0, v5
	v_rcp_iflag_f32_e32 v11, v11
	v_add_u32_e32 v12, s13, v3
	v_mul_f32_e32 v11, 0x4f7ffffe, v11
	v_cvt_u32_f32_e32 v11, v11
	v_mul_lo_u32 v3, v10, v11
	v_mul_hi_u32 v3, v11, v3
	v_add_u32_e32 v3, v11, v3
	v_mul_hi_u32 v3, v12, v3
	v_mul_lo_u32 v10, v3, v5
	v_sub_u32_e32 v10, v12, v10
	v_add_u32_e32 v11, 1, v3
	v_cmp_ge_u32_e32 vcc, v10, v5
	s_nop 1
	v_cndmask_b32_e32 v3, v3, v11, vcc
	v_sub_u32_e32 v11, v10, v5
	v_cndmask_b32_e32 v10, v10, v11, vcc
	v_add_u32_e32 v11, 1, v3
	v_cmp_ge_u32_e32 vcc, v10, v5
	v_add_u32_e32 v10, 1, v12
	s_nop 0
	v_cndmask_b32_e32 v3, v3, v11, vcc
	v_mul_lo_u32 v11, v5, v3
	v_add_u32_e32 v5, v11, v5
	v_cmp_ne_u32_e32 vcc, v10, v5
	s_and_saveexec_b64 s[14:15], vcc
	s_xor_b64 s[36:37], exec, s[14:15]
	s_cbranch_execz .LBB0_789
	s_movk_i32 s26, 0xd40
	buffer_inv sc1
	s_lshl_b64 s[14:15], s[26:27], 2
	s_add_u32 s74, s70, s14
	s_addc_u32 s75, s71, s15
	s_waitcnt lgkmcnt(0)
	global_load_dword v4, v2, s[74:75] sc1
	s_waitcnt vmcnt(0)
	v_cmp_eq_u32_e32 vcc, v4, v3
	s_and_saveexec_b64 s[38:39], vcc
	s_cbranch_execz .LBB0_788
	s_mov_b32 s13, 1
	s_mov_b64 s[76:77], 0
	s_branch .LBB0_779

.LBB0_788:
	s_or_b64 exec, exec, s[38:39]
	s_waitcnt vmcnt(0)
	s_waitcnt vmcnt(0)
.LBB0_789:
	s_andn2_saveexec_b64 s[14:15], s[36:37]
	s_cbranch_execz .LBB0_809
	s_mov_b64 s[36:37], exec
	buffer_wbl2 sc1
	buffer_inv sc1
	s_waitcnt lgkmcnt(0)
	s_waitcnt vmcnt(0)
	v_mbcnt_lo_u32_b32 v3, s36, 0
	v_mbcnt_hi_u32_b32 v3, s37, v3
	v_cmp_eq_u32_e32 vcc, 0, v3
	s_and_saveexec_b64 s[38:39], vcc
	s_cbranch_execz .LBB0_792
	s_bcnt1_i32_b64 s13, s[36:37]
	v_mov_b32_e32 v5, s13
	global_atomic_add v5, v172, v5, s[70:71] offset:1024 sc0

.LBB0_806:
	s_or_b64 exec, exec, s[36:37]
	s_mov_b64 s[36:37], exec
	v_mbcnt_lo_u32_b32 v3, s36, 0
	v_mbcnt_hi_u32_b32 v3, s37, v3
	v_cmp_eq_u32_e32 vcc, 0, v3
	s_waitcnt vmcnt(0)
	s_and_saveexec_b64 s[38:39], vcc
	s_cbranch_execz .LBB0_808
	s_add_i32 s26, s12, 0x900
	s_lshl_b64 s[12:13], s[26:27], 2
	s_add_u32 s12, s70, s12
	s_addc_u32 s13, s71, s13
	s_bcnt1_i32_b64 s14, s[36:37]
	v_mov_b32_e32 v3, s14
	s_nop 0

.LBB0_896:
	s_or_b64 exec, exec, s[8:9]
	v_cvt_f32_u32_e32 v10, v4
	s_waitcnt vmcnt(0)
	v_readfirstlane_b32 s6, v5
	v_sub_u32_e32 v5, 0, v4
	v_rcp_iflag_f32_e32 v10, v10
	v_add_u32_e32 v11, s6, v3
	v_mul_f32_e32 v10, 0x4f7ffffe, v10
	v_cvt_u32_f32_e32 v10, v10
	v_mul_lo_u32 v3, v5, v10
	v_mul_hi_u32 v3, v10, v3
	v_add_u32_e32 v3, v10, v3
	v_mul_hi_u32 v3, v11, v3
	v_mul_lo_u32 v5, v3, v4
	v_sub_u32_e32 v5, v11, v5
	v_add_u32_e32 v10, 1, v3
	v_cmp_ge_u32_e32 vcc, v5, v4
	s_nop 1
	v_cndmask_b32_e32 v3, v3, v10, vcc
	v_sub_u32_e32 v10, v5, v4
	v_cndmask_b32_e32 v5, v5, v10, vcc
	v_add_u32_e32 v10, 1, v3
	v_cmp_ge_u32_e32 vcc, v5, v4
	v_add_u32_e32 v5, 1, v11
	s_nop 0
	v_cndmask_b32_e32 v3, v3, v10, vcc
	v_mul_lo_u32 v10, v4, v3
	v_add_u32_e32 v4, v10, v4
	v_cmp_ne_u32_e32 vcc, v5, v4
	s_and_saveexec_b64 s[6:7], vcc
	s_xor_b64 s[6:7], exec, s[6:7]
	s_cbranch_execz .LBB0_910
	s_movk_i32 s26, 0xd40
	buffer_inv sc1
	s_lshl_b64 s[8:9], s[26:27], 2
	s_add_u32 s10, s4, s8
	s_addc_u32 s11, s5, s9
	s_waitcnt lgkmcnt(0)
	global_load_dword v1, v2, s[10:11] sc1
	s_waitcnt vmcnt(0)
	v_cmp_eq_u32_e32 vcc, v1, v3
	s_and_saveexec_b64 s[8:9], vcc
	s_cbranch_execz .LBB0_909
	s_mov_b32 s13, 1
	s_mov_b64 s[36:37], 0
	s_branch .LBB0_900

.LBB0_910:
	s_andn2_saveexec_b64 s[6:7], s[6:7]
	s_cbranch_execz .LBB0_519
	s_mov_b64 s[6:7], exec
	buffer_wbl2 sc1
	buffer_inv sc1
	s_waitcnt lgkmcnt(0)
	s_waitcnt vmcnt(0)
	v_mbcnt_lo_u32_b32 v3, s6, 0
	v_mbcnt_hi_u32_b32 v3, s7, v3
	v_cmp_eq_u32_e32 vcc, 0, v3
	s_and_saveexec_b64 s[8:9], vcc
	s_cbranch_execz .LBB0_913
	s_bcnt1_i32_b64 s6, s[6:7]
	v_mov_b32_e32 v4, s6
	global_atomic_add v4, v172, v4, s[4:5] offset:1024 sc0

.LBB0_927:
	s_or_b64 exec, exec, s[6:7]
	s_mov_b64 s[6:7], exec
	v_mbcnt_lo_u32_b32 v1, s6, 0
	v_mbcnt_hi_u32_b32 v1, s7, v1
	v_cmp_eq_u32_e32 vcc, 0, v1
	s_waitcnt vmcnt(0)
	s_and_saveexec_b64 s[8:9], vcc
	s_cbranch_execz .LBB0_518
	s_add_i32 s26, s12, 0x900
	s_lshl_b64 s[10:11], s[26:27], 2
	s_add_u32 s4, s4, s10
	s_addc_u32 s5, s5, s11
	s_bcnt1_i32_b64 s6, s[6:7]
	v_mov_b32_e32 v1, s6
	s_nop 0
	s_branch .LBB0_518
